# v63 + 8 bytes of unreachable padding before the attention loops (placement shift, byte phase mod 8 unchanged)
# speedup vs baseline: 1.0063x; 1.0063x over previous
.LBB0_381:
	v_lshrrev_b32_e32 v0, 2, v81
	v_exp_f32_e32 v3, v84
	v_exp_f32_e32 v7, v83
	v_exp_f32_e32 v6, v49
	v_exp_f32_e32 v11, v48
	v_exp_f32_e32 v10, v51
	v_exp_f32_e32 v96, v50
	v_exp_f32_e32 v15, v53
	v_exp_f32_e32 v97, v52
	v_exp_f32_e32 v2, v55
	v_exp_f32_e32 v5, v54
	v_exp_f32_e32 v4, v57
	v_exp_f32_e32 v9, v56
	v_exp_f32_e32 v8, v59
	v_exp_f32_e32 v12, v58
	v_exp_f32_e32 v13, v61
	v_exp_f32_e32 v14, v60
	s_min_i32 s2, s29, 26
	v_and_or_b32 v0, v0, 3, v158
	v_lshlrev_b32_e32 v62, 1, v81
	s_sub_i32 s54, s2, s5
	v_lshlrev_b32_e32 v0, 6, v0
	v_and_b32_e32 v48, 32, v62
	v_mov_b32_e32 v155, v154
	s_mov_b32 s29, 1
	s_cmp_lt_i32 s54, -5
	v_or3_b32 v0, v48, v0, v82
	s_cbranch_scc1 .LBB0_391
	v_lshl_or_b32 v48, s5, 6, v158
	v_sub_u32_e32 v48, v48, v80
	v_subrev_u32_e32 v48, s53, v48
	s_lshl_b32 s2, s30, 8
	v_subrev_u32_e32 v162, s2, v48
	v_mov_b64_e32 v[62:63], v[46:47]
	s_add_i32 s54, s54, 8
	s_mov_b32 s30, 0x8000
	s_movk_i32 s53, 0x4000
	s_mov_b32 s2, 0
	s_mov_b32 s29, 3
	v_mov_b64_e32 v[60:61], v[44:45]
	v_mov_b64_e32 v[58:59], v[42:43]
	v_mov_b64_e32 v[56:57], v[40:41]
	v_mov_b64_e32 v[54:55], v[38:39]
	v_mov_b64_e32 v[52:53], v[36:37]
	v_mov_b64_e32 v[50:51], v[34:35]
	v_mov_b64_e32 v[48:49], v[32:33]
	s_branch .LBB0_383
	s_nop 0
	s_nop 0
